# top-k selection loop rewritten branch-free: wave max via DPP/permlane ladder then min index among maxima (8 queries interleaved)
# speedup vs baseline: 1.0100x; 1.0100x over previous
; template <int CTRL> __device__ __forceinline__ int dppi(int v) { return __builtin_amdgcn_update_dpp(v, v, CTRL, 0xF, 0xF, false); }
; template <int CTRL> __device__ __forceinline__ float dppf(float v) { return __int_as_float(dppi<CTRL>(__float_as_int(v))); }
; __device__ __forceinline__ void amax_merge(float& bv, int& bj, float ov, int oj) { if (ov > bv || (ov == bv && oj < bj)) { bv = ov; bj = oj; } }
; __device__ __forceinline__ void wave_argmax(float& bv, int& bj) {
;     typedef unsigned u2v __attribute__((ext_vector_type(2)));
;     amax_merge(bv, bj, dppf<0xB1>(bv), dppi<0xB1>(bj));
;     amax_merge(bv, bj, dppf<0x4E>(bv), dppi<0x4E>(bj));
;     amax_merge(bv, bj, dppf<0x141>(bv), dppi<0x141>(bj));
;     amax_merge(bv, bj, dppf<0x140>(bv), dppi<0x140>(bj));
;     {
;         const u2v rv = __builtin_amdgcn_permlane16_swap(__float_as_uint(bv), __float_as_uint(bv), false, false);
;         const u2v rj = __builtin_amdgcn_permlane16_swap((unsigned)bj, (unsigned)bj, false, false);
;         float av = __uint_as_float(rv[0]); int aj = (int)rj[0];
;         amax_merge(av, aj, __uint_as_float(rv[1]), (int)rj[1]); bv = av; bj = aj;
;     }
;     {
;         const u2v rv = __builtin_amdgcn_permlane32_swap(__float_as_uint(bv), __float_as_uint(bv), false, false);
;         const u2v rj = __builtin_amdgcn_permlane32_swap((unsigned)bj, (unsigned)bj, false, false);
;         float av = __uint_as_float(rv[0]); int aj = (int)rj[0];
;         amax_merge(av, aj, __uint_as_float(rv[1]), (int)rj[1]); bv = av; bj = aj;
;     }
; }
; __device__ __forceinline__ void cmp_item(CPR P, LAS unsigned char* lds, int kvh, int qt) {
;     ...
;             for (int qi = 0; qi < 8; ++qi) {
;                 bv[qi] = -3e38f; bj[qi] = 1 << 20;
; #pragma unroll
;                 for (int i = 0; i < 4; ++i) if (!((sel[qi] >> i) & 1u) && sc[qi][i] > bv[qi]) { bv[qi] = sc[qi][i]; bj[qi] = i * 64 + lane; }
;             }
; #pragma unroll
;             for (int qi = 0; qi < 8; ++qi) wave_argmax(bv[qi], bj[qi]);
.LBB0_2301:
	v_and_b32_e32 v80, 1, v49
	v_cmp_eq_u32_e64 s[18:19], 0, v80
	v_cmp_gt_f32_e64 s[20:21], v7, v224
	s_and_b64 s[18:19], s[18:19], s[20:21]
	v_cndmask_b32_e64 v64, v224, v7, s[18:19]
	v_cndmask_b32_e64 v65, v225, v227, s[18:19]
	v_and_b32_e32 v80, 2, v49
	v_cmp_eq_u32_e64 s[18:19], 0, v80
	v_cmp_gt_f32_e64 s[20:21], v11, v64
	s_and_b64 s[18:19], s[18:19], s[20:21]
	v_cndmask_b32_e64 v64, v64, v11, s[18:19]
	v_cndmask_b32_e64 v65, v65, v9, s[18:19]
	v_and_b32_e32 v80, 4, v49
	v_cmp_eq_u32_e64 s[18:19], 0, v80
	v_cmp_gt_f32_e64 s[20:21], v15, v64
	s_and_b64 s[18:19], s[18:19], s[20:21]
	v_cndmask_b32_e64 v64, v64, v15, s[18:19]
	v_cndmask_b32_e64 v65, v65, v13, s[18:19]
	v_and_b32_e32 v80, 8, v49
	v_cmp_eq_u32_e64 s[18:19], 0, v80
	v_cmp_gt_f32_e64 s[20:21], v18, v64
	s_and_b64 s[18:19], s[18:19], s[20:21]
	v_cndmask_b32_e64 v64, v64, v18, s[18:19]
	v_cndmask_b32_e64 v65, v65, v17, s[18:19]
	v_and_b32_e32 v82, 1, v42
	v_cmp_eq_u32_e64 s[38:39], 0, v82
	v_cmp_gt_f32_e64 s[48:49], v19, v224
	s_and_b64 s[38:39], s[38:39], s[48:49]
	v_cndmask_b32_e64 v66, v224, v19, s[38:39]
	v_cndmask_b32_e64 v67, v225, v227, s[38:39]
	v_and_b32_e32 v82, 2, v42
	v_cmp_eq_u32_e64 s[38:39], 0, v82
	v_cmp_gt_f32_e64 s[48:49], v21, v66
	s_and_b64 s[38:39], s[38:39], s[48:49]
	v_cndmask_b32_e64 v66, v66, v21, s[38:39]
	v_cndmask_b32_e64 v67, v67, v9, s[38:39]
	v_and_b32_e32 v82, 4, v42
	v_cmp_eq_u32_e64 s[38:39], 0, v82
	v_cmp_gt_f32_e64 s[48:49], v22, v66
	s_and_b64 s[38:39], s[38:39], s[48:49]
	v_cndmask_b32_e64 v66, v66, v22, s[38:39]
	v_cndmask_b32_e64 v67, v67, v13, s[38:39]
	v_and_b32_e32 v82, 8, v42
	v_cmp_eq_u32_e64 s[38:39], 0, v82
	v_cmp_gt_f32_e64 s[48:49], v23, v66
	s_and_b64 s[38:39], s[38:39], s[48:49]
	v_cndmask_b32_e64 v66, v66, v23, s[38:39]
	v_cndmask_b32_e64 v67, v67, v17, s[38:39]
	v_and_b32_e32 v84, 1, v33
	v_cmp_eq_u32_e64 s[18:19], 0, v84
	v_cmp_gt_f32_e64 s[20:21], v25, v224
	s_and_b64 s[18:19], s[18:19], s[20:21]
	v_cndmask_b32_e64 v68, v224, v25, s[18:19]
	v_cndmask_b32_e64 v69, v225, v227, s[18:19]
	v_and_b32_e32 v84, 2, v33
	v_cmp_eq_u32_e64 s[18:19], 0, v84
	v_cmp_gt_f32_e64 s[20:21], v26, v68
	s_and_b64 s[18:19], s[18:19], s[20:21]
	v_cndmask_b32_e64 v68, v68, v26, s[18:19]
	v_cndmask_b32_e64 v69, v69, v9, s[18:19]
	v_and_b32_e32 v84, 4, v33
	v_cmp_eq_u32_e64 s[18:19], 0, v84
	v_cmp_gt_f32_e64 s[20:21], v27, v68
	s_and_b64 s[18:19], s[18:19], s[20:21]
	v_cndmask_b32_e64 v68, v68, v27, s[18:19]
	v_cndmask_b32_e64 v69, v69, v13, s[18:19]
	v_and_b32_e32 v84, 8, v33
	v_cmp_eq_u32_e64 s[18:19], 0, v84
	v_cmp_gt_f32_e64 s[20:21], v28, v68
	s_and_b64 s[18:19], s[18:19], s[20:21]
	v_cndmask_b32_e64 v68, v68, v28, s[18:19]
	v_cndmask_b32_e64 v69, v69, v17, s[18:19]
	v_and_b32_e32 v86, 1, v24
	v_cmp_eq_u32_e64 s[38:39], 0, v86
	v_cmp_gt_f32_e64 s[48:49], v29, v224
	s_and_b64 s[38:39], s[38:39], s[48:49]
	v_cndmask_b32_e64 v70, v224, v29, s[38:39]
	v_cndmask_b32_e64 v71, v225, v227, s[38:39]
	v_and_b32_e32 v86, 2, v24
	v_cmp_eq_u32_e64 s[38:39], 0, v86
	v_cmp_gt_f32_e64 s[48:49], v30, v70
	s_and_b64 s[38:39], s[38:39], s[48:49]
	v_cndmask_b32_e64 v70, v70, v30, s[38:39]
	v_cndmask_b32_e64 v71, v71, v9, s[38:39]
	v_and_b32_e32 v86, 4, v24
	v_cmp_eq_u32_e64 s[38:39], 0, v86
	v_cmp_gt_f32_e64 s[48:49], v31, v70
	s_and_b64 s[38:39], s[38:39], s[48:49]
	v_cndmask_b32_e64 v70, v70, v31, s[38:39]
	v_cndmask_b32_e64 v71, v71, v13, s[38:39]
	v_and_b32_e32 v86, 8, v24
	v_cmp_eq_u32_e64 s[38:39], 0, v86
	v_cmp_gt_f32_e64 s[48:49], v32, v70
	s_and_b64 s[38:39], s[38:39], s[48:49]
	v_cndmask_b32_e64 v70, v70, v32, s[38:39]
	v_cndmask_b32_e64 v71, v71, v17, s[38:39]
	v_and_b32_e32 v88, 1, v20
	v_cmp_eq_u32_e64 s[18:19], 0, v88
	v_cmp_gt_f32_e64 s[20:21], v34, v224
	s_and_b64 s[18:19], s[18:19], s[20:21]
	v_cndmask_b32_e64 v72, v224, v34, s[18:19]
	v_cndmask_b32_e64 v73, v225, v227, s[18:19]
	v_and_b32_e32 v88, 2, v20
	v_cmp_eq_u32_e64 s[18:19], 0, v88
	v_cmp_gt_f32_e64 s[20:21], v35, v72
	s_and_b64 s[18:19], s[18:19], s[20:21]
	v_cndmask_b32_e64 v72, v72, v35, s[18:19]
	v_cndmask_b32_e64 v73, v73, v9, s[18:19]
	v_and_b32_e32 v88, 4, v20
	v_cmp_eq_u32_e64 s[18:19], 0, v88
	v_cmp_gt_f32_e64 s[20:21], v36, v72
	s_and_b64 s[18:19], s[18:19], s[20:21]
	v_cndmask_b32_e64 v72, v72, v36, s[18:19]
	v_cndmask_b32_e64 v73, v73, v13, s[18:19]
	v_and_b32_e32 v88, 8, v20
	v_cmp_eq_u32_e64 s[18:19], 0, v88
	v_cmp_gt_f32_e64 s[20:21], v37, v72
	s_and_b64 s[18:19], s[18:19], s[20:21]
	v_cndmask_b32_e64 v72, v72, v37, s[18:19]
	v_cndmask_b32_e64 v73, v73, v17, s[18:19]
	v_and_b32_e32 v90, 1, v5
	v_cmp_eq_u32_e64 s[38:39], 0, v90
	v_cmp_gt_f32_e64 s[48:49], v38, v224
	s_and_b64 s[38:39], s[38:39], s[48:49]
	v_cndmask_b32_e64 v74, v224, v38, s[38:39]
	v_cndmask_b32_e64 v75, v225, v227, s[38:39]
	v_and_b32_e32 v90, 2, v5
	v_cmp_eq_u32_e64 s[38:39], 0, v90
	v_cmp_gt_f32_e64 s[48:49], v39, v74
	s_and_b64 s[38:39], s[38:39], s[48:49]
	v_cndmask_b32_e64 v74, v74, v39, s[38:39]
	v_cndmask_b32_e64 v75, v75, v9, s[38:39]
	v_and_b32_e32 v90, 4, v5
	v_cmp_eq_u32_e64 s[38:39], 0, v90
	v_cmp_gt_f32_e64 s[48:49], v40, v74
	s_and_b64 s[38:39], s[38:39], s[48:49]
	v_cndmask_b32_e64 v74, v74, v40, s[38:39]
	v_cndmask_b32_e64 v75, v75, v13, s[38:39]
	v_and_b32_e32 v90, 8, v5
	v_cmp_eq_u32_e64 s[38:39], 0, v90
	v_cmp_gt_f32_e64 s[48:49], v41, v74
	s_and_b64 s[38:39], s[38:39], s[48:49]
	v_cndmask_b32_e64 v74, v74, v41, s[38:39]
	v_cndmask_b32_e64 v75, v75, v17, s[38:39]
	v_and_b32_e32 v92, 1, v2
	v_cmp_eq_u32_e64 s[18:19], 0, v92
	v_cmp_gt_f32_e64 s[20:21], v43, v224
	s_and_b64 s[18:19], s[18:19], s[20:21]
	v_cndmask_b32_e64 v76, v224, v43, s[18:19]
	v_cndmask_b32_e64 v77, v225, v227, s[18:19]
; template <int CTRL> __device__ __forceinline__ int dppi(int v) { return __builtin_amdgcn_update_dpp(v, v, CTRL, 0xF, 0xF, false); }
; template <int CTRL> __device__ __forceinline__ float dppf(float v) { return __int_as_float(dppi<CTRL>(__float_as_int(v))); }
; __device__ __forceinline__ void amax_merge(float& bv, int& bj, float ov, int oj) { if (ov > bv || (ov == bv && oj < bj)) { bv = ov; bj = oj; } }
; __device__ __forceinline__ void wave_argmax(float& bv, int& bj) {
;     typedef unsigned u2v __attribute__((ext_vector_type(2)));
;     amax_merge(bv, bj, dppf<0xB1>(bv), dppi<0xB1>(bj));
;     amax_merge(bv, bj, dppf<0x4E>(bv), dppi<0x4E>(bj));
;     amax_merge(bv, bj, dppf<0x141>(bv), dppi<0x141>(bj));
;     amax_merge(bv, bj, dppf<0x140>(bv), dppi<0x140>(bj));
;     {
;         const u2v rv = __builtin_amdgcn_permlane16_swap(__float_as_uint(bv), __float_as_uint(bv), false, false);
;         const u2v rj = __builtin_amdgcn_permlane16_swap((unsigned)bj, (unsigned)bj, false, false);
;         float av = __uint_as_float(rv[0]); int aj = (int)rj[0];
;         amax_merge(av, aj, __uint_as_float(rv[1]), (int)rj[1]); bv = av; bj = aj;
;     }
;     {
;         const u2v rv = __builtin_amdgcn_permlane32_swap(__float_as_uint(bv), __float_as_uint(bv), false, false);
;         const u2v rj = __builtin_amdgcn_permlane32_swap((unsigned)bj, (unsigned)bj, false, false);
;         float av = __uint_as_float(rv[0]); int aj = (int)rj[0];
;         amax_merge(av, aj, __uint_as_float(rv[1]), (int)rj[1]); bv = av; bj = aj;
;     }
; }
; __device__ __forceinline__ void cmp_item(CPR P, LAS unsigned char* lds, int kvh, int qt) {
;     ...
;             for (int qi = 0; qi < 8; ++qi) {
;                 bv[qi] = -3e38f; bj[qi] = 1 << 20;
; #pragma unroll
;                 for (int i = 0; i < 4; ++i) if (!((sel[qi] >> i) & 1u) && sc[qi][i] > bv[qi]) { bv[qi] = sc[qi][i]; bj[qi] = i * 64 + lane; }
;             }
; #pragma unroll
;             for (int qi = 0; qi < 8; ++qi) wave_argmax(bv[qi], bj[qi]);
	v_and_b32_e32 v92, 2, v2
	v_cmp_eq_u32_e64 s[18:19], 0, v92
	v_cmp_gt_f32_e64 s[20:21], v44, v76
	s_and_b64 s[18:19], s[18:19], s[20:21]
	v_cndmask_b32_e64 v76, v76, v44, s[18:19]
	v_cndmask_b32_e64 v77, v77, v9, s[18:19]
	v_and_b32_e32 v92, 4, v2
	v_cmp_eq_u32_e64 s[18:19], 0, v92
	v_cmp_gt_f32_e64 s[20:21], v45, v76
	s_and_b64 s[18:19], s[18:19], s[20:21]
	v_cndmask_b32_e64 v76, v76, v45, s[18:19]
	v_cndmask_b32_e64 v77, v77, v13, s[18:19]
	v_and_b32_e32 v92, 8, v2
	v_cmp_eq_u32_e64 s[18:19], 0, v92
	v_cmp_gt_f32_e64 s[20:21], v46, v76
	s_and_b64 s[18:19], s[18:19], s[20:21]
	v_cndmask_b32_e64 v76, v76, v46, s[18:19]
	v_cndmask_b32_e64 v77, v77, v17, s[18:19]
	v_and_b32_e32 v94, 1, v1
	v_cmp_eq_u32_e64 s[38:39], 0, v94
	v_cmp_gt_f32_e64 s[48:49], v47, v224
	s_and_b64 s[38:39], s[38:39], s[48:49]
	v_cndmask_b32_e64 v78, v224, v47, s[38:39]
	v_cndmask_b32_e64 v79, v225, v227, s[38:39]
	v_and_b32_e32 v94, 2, v1
	v_cmp_eq_u32_e64 s[38:39], 0, v94
	v_cmp_gt_f32_e64 s[48:49], v48, v78
	s_and_b64 s[38:39], s[38:39], s[48:49]
	v_cndmask_b32_e64 v78, v78, v48, s[38:39]
	v_cndmask_b32_e64 v79, v79, v9, s[38:39]
	v_and_b32_e32 v94, 4, v1
	v_cmp_eq_u32_e64 s[38:39], 0, v94
	v_cmp_gt_f32_e64 s[48:49], v50, v78
	s_and_b64 s[38:39], s[38:39], s[48:49]
	v_cndmask_b32_e64 v78, v78, v50, s[38:39]
	v_cndmask_b32_e64 v79, v79, v13, s[38:39]
	v_and_b32_e32 v94, 8, v1
	v_cmp_eq_u32_e64 s[38:39], 0, v94
	v_cmp_gt_f32_e64 s[48:49], v51, v78
	s_and_b64 s[38:39], s[38:39], s[48:49]
	v_cndmask_b32_e64 v78, v78, v51, s[38:39]
	v_cndmask_b32_e64 v79, v79, v17, s[38:39]
	v_max_f32_dpp v80, v64, v64 quad_perm:[1,0,3,2] row_mask:0xf bank_mask:0xf
	v_max_f32_dpp v82, v66, v66 quad_perm:[1,0,3,2] row_mask:0xf bank_mask:0xf
	v_max_f32_dpp v84, v68, v68 quad_perm:[1,0,3,2] row_mask:0xf bank_mask:0xf
	v_max_f32_dpp v86, v70, v70 quad_perm:[1,0,3,2] row_mask:0xf bank_mask:0xf
	v_max_f32_dpp v88, v72, v72 quad_perm:[1,0,3,2] row_mask:0xf bank_mask:0xf
	v_max_f32_dpp v90, v74, v74 quad_perm:[1,0,3,2] row_mask:0xf bank_mask:0xf
	v_max_f32_dpp v92, v76, v76 quad_perm:[1,0,3,2] row_mask:0xf bank_mask:0xf
	v_max_f32_dpp v94, v78, v78 quad_perm:[1,0,3,2] row_mask:0xf bank_mask:0xf
	v_max_f32_dpp v81, v80, v80 quad_perm:[2,3,0,1] row_mask:0xf bank_mask:0xf
	v_max_f32_dpp v83, v82, v82 quad_perm:[2,3,0,1] row_mask:0xf bank_mask:0xf
	v_max_f32_dpp v85, v84, v84 quad_perm:[2,3,0,1] row_mask:0xf bank_mask:0xf
	v_max_f32_dpp v87, v86, v86 quad_perm:[2,3,0,1] row_mask:0xf bank_mask:0xf
	v_max_f32_dpp v89, v88, v88 quad_perm:[2,3,0,1] row_mask:0xf bank_mask:0xf
	v_max_f32_dpp v91, v90, v90 quad_perm:[2,3,0,1] row_mask:0xf bank_mask:0xf
	v_max_f32_dpp v93, v92, v92 quad_perm:[2,3,0,1] row_mask:0xf bank_mask:0xf
	v_max_f32_dpp v95, v94, v94 quad_perm:[2,3,0,1] row_mask:0xf bank_mask:0xf
	v_max_f32_dpp v80, v81, v81 row_half_mirror row_mask:0xf bank_mask:0xf
	v_max_f32_dpp v82, v83, v83 row_half_mirror row_mask:0xf bank_mask:0xf
	v_max_f32_dpp v84, v85, v85 row_half_mirror row_mask:0xf bank_mask:0xf
	v_max_f32_dpp v86, v87, v87 row_half_mirror row_mask:0xf bank_mask:0xf
	v_max_f32_dpp v88, v89, v89 row_half_mirror row_mask:0xf bank_mask:0xf
	v_max_f32_dpp v90, v91, v91 row_half_mirror row_mask:0xf bank_mask:0xf
	v_max_f32_dpp v92, v93, v93 row_half_mirror row_mask:0xf bank_mask:0xf
	v_max_f32_dpp v94, v95, v95 row_half_mirror row_mask:0xf bank_mask:0xf
	v_max_f32_dpp v81, v80, v80 row_mirror row_mask:0xf bank_mask:0xf
	v_max_f32_dpp v83, v82, v82 row_mirror row_mask:0xf bank_mask:0xf
	v_max_f32_dpp v85, v84, v84 row_mirror row_mask:0xf bank_mask:0xf
	v_max_f32_dpp v87, v86, v86 row_mirror row_mask:0xf bank_mask:0xf
	v_max_f32_dpp v89, v88, v88 row_mirror row_mask:0xf bank_mask:0xf
	v_max_f32_dpp v91, v90, v90 row_mirror row_mask:0xf bank_mask:0xf
	v_max_f32_dpp v93, v92, v92 row_mirror row_mask:0xf bank_mask:0xf
	v_max_f32_dpp v95, v94, v94 row_mirror row_mask:0xf bank_mask:0xf
	v_mov_b32_e32 v80, v81
	v_mov_b32_e32 v82, v83
	v_mov_b32_e32 v84, v85
	v_mov_b32_e32 v86, v87
	v_mov_b32_e32 v88, v89
	v_mov_b32_e32 v90, v91
	v_mov_b32_e32 v92, v93
	v_mov_b32_e32 v94, v95
	v_permlane16_swap_b32_e32 v81, v80
	v_permlane16_swap_b32_e32 v83, v82
	v_permlane16_swap_b32_e32 v85, v84
	v_permlane16_swap_b32_e32 v87, v86
	v_permlane16_swap_b32_e32 v89, v88
	v_permlane16_swap_b32_e32 v91, v90
	v_permlane16_swap_b32_e32 v93, v92
	v_permlane16_swap_b32_e32 v95, v94
	v_max_f32_e32 v81, v81, v80
	v_max_f32_e32 v83, v83, v82
	v_max_f32_e32 v85, v85, v84
	v_max_f32_e32 v87, v87, v86
	v_max_f32_e32 v89, v89, v88
	v_max_f32_e32 v91, v91, v90
	v_max_f32_e32 v93, v93, v92
	v_max_f32_e32 v95, v95, v94
	v_mov_b32_e32 v80, v81
	v_mov_b32_e32 v82, v83
	v_mov_b32_e32 v84, v85
	v_mov_b32_e32 v86, v87
	v_mov_b32_e32 v88, v89
	v_mov_b32_e32 v90, v91
	v_mov_b32_e32 v92, v93
	v_mov_b32_e32 v94, v95
	v_permlane32_swap_b32_e32 v81, v80
	v_permlane32_swap_b32_e32 v83, v82
	v_permlane32_swap_b32_e32 v85, v84
	v_permlane32_swap_b32_e32 v87, v86
	v_permlane32_swap_b32_e32 v89, v88
	v_permlane32_swap_b32_e32 v91, v90
	v_permlane32_swap_b32_e32 v93, v92
	v_permlane32_swap_b32_e32 v95, v94
	v_max_f32_e32 v96, v81, v80
	v_max_f32_e32 v97, v83, v82
	v_max_f32_e32 v98, v85, v84
	v_max_f32_e32 v99, v87, v86
	v_max_f32_e32 v100, v89, v88
	v_max_f32_e32 v101, v91, v90
	v_max_f32_e32 v102, v93, v92
	v_max_f32_e32 v103, v95, v94
	v_cmp_eq_f32_e64 s[4:5], v64, v96
	v_cmp_eq_f32_e64 s[6:7], v66, v97
	v_cmp_eq_f32_e64 s[8:9], v68, v98
	v_cmp_eq_f32_e64 s[10:11], v70, v99
	v_cmp_eq_f32_e64 s[12:13], v72, v100
	v_cmp_eq_f32_e64 s[14:15], v74, v101
	v_cmp_eq_f32_e64 s[16:17], v76, v102
	v_cmp_eq_f32_e64 s[18:19], v78, v103
; template <int CTRL> __device__ __forceinline__ int dppi(int v) { return __builtin_amdgcn_update_dpp(v, v, CTRL, 0xF, 0xF, false); }
; template <int CTRL> __device__ __forceinline__ float dppf(float v) { return __int_as_float(dppi<CTRL>(__float_as_int(v))); }
; __device__ __forceinline__ void amax_merge(float& bv, int& bj, float ov, int oj) { if (ov > bv || (ov == bv && oj < bj)) { bv = ov; bj = oj; } }
; __device__ __forceinline__ void wave_argmax(float& bv, int& bj) {
;     typedef unsigned u2v __attribute__((ext_vector_type(2)));
;     amax_merge(bv, bj, dppf<0xB1>(bv), dppi<0xB1>(bj));
;     amax_merge(bv, bj, dppf<0x4E>(bv), dppi<0x4E>(bj));
;     amax_merge(bv, bj, dppf<0x141>(bv), dppi<0x141>(bj));
;     amax_merge(bv, bj, dppf<0x140>(bv), dppi<0x140>(bj));
;     {
;         const u2v rv = __builtin_amdgcn_permlane16_swap(__float_as_uint(bv), __float_as_uint(bv), false, false);
;         const u2v rj = __builtin_amdgcn_permlane16_swap((unsigned)bj, (unsigned)bj, false, false);
;         float av = __uint_as_float(rv[0]); int aj = (int)rj[0];
;         amax_merge(av, aj, __uint_as_float(rv[1]), (int)rj[1]); bv = av; bj = aj;
;     }
;     {
;         const u2v rv = __builtin_amdgcn_permlane32_swap(__float_as_uint(bv), __float_as_uint(bv), false, false);
;         const u2v rj = __builtin_amdgcn_permlane32_swap((unsigned)bj, (unsigned)bj, false, false);
;         float av = __uint_as_float(rv[0]); int aj = (int)rj[0];
;         amax_merge(av, aj, __uint_as_float(rv[1]), (int)rj[1]); bv = av; bj = aj;
;     }
; }
; __device__ __forceinline__ void cmp_item(CPR P, LAS unsigned char* lds, int kvh, int qt) {
;     ...
;             for (int qi = 0; qi < 8; ++qi) wave_argmax(bv[qi], bj[qi]);
; #pragma unroll
;             for (int qi = 0; qi < 8; ++qi) if ((bj[qi] & 63) == lane) sel[qi] |= 1u << (bj[qi] >> 6);
;         }
	v_cndmask_b32_e64 v64, v225, v65, s[4:5]
	v_cndmask_b32_e64 v66, v225, v67, s[6:7]
	v_cndmask_b32_e64 v68, v225, v69, s[8:9]
	v_cndmask_b32_e64 v70, v225, v71, s[10:11]
	v_cndmask_b32_e64 v72, v225, v73, s[12:13]
	v_cndmask_b32_e64 v74, v225, v75, s[14:15]
	v_cndmask_b32_e64 v76, v225, v77, s[16:17]
	v_cndmask_b32_e64 v78, v225, v79, s[18:19]
	v_min_u32_dpp v80, v64, v64 quad_perm:[1,0,3,2] row_mask:0xf bank_mask:0xf
	v_min_u32_dpp v82, v66, v66 quad_perm:[1,0,3,2] row_mask:0xf bank_mask:0xf
	v_min_u32_dpp v84, v68, v68 quad_perm:[1,0,3,2] row_mask:0xf bank_mask:0xf
	v_min_u32_dpp v86, v70, v70 quad_perm:[1,0,3,2] row_mask:0xf bank_mask:0xf
	v_min_u32_dpp v88, v72, v72 quad_perm:[1,0,3,2] row_mask:0xf bank_mask:0xf
	v_min_u32_dpp v90, v74, v74 quad_perm:[1,0,3,2] row_mask:0xf bank_mask:0xf
	v_min_u32_dpp v92, v76, v76 quad_perm:[1,0,3,2] row_mask:0xf bank_mask:0xf
	v_min_u32_dpp v94, v78, v78 quad_perm:[1,0,3,2] row_mask:0xf bank_mask:0xf
	v_min_u32_dpp v81, v80, v80 quad_perm:[2,3,0,1] row_mask:0xf bank_mask:0xf
	v_min_u32_dpp v83, v82, v82 quad_perm:[2,3,0,1] row_mask:0xf bank_mask:0xf
	v_min_u32_dpp v85, v84, v84 quad_perm:[2,3,0,1] row_mask:0xf bank_mask:0xf
	v_min_u32_dpp v87, v86, v86 quad_perm:[2,3,0,1] row_mask:0xf bank_mask:0xf
	v_min_u32_dpp v89, v88, v88 quad_perm:[2,3,0,1] row_mask:0xf bank_mask:0xf
	v_min_u32_dpp v91, v90, v90 quad_perm:[2,3,0,1] row_mask:0xf bank_mask:0xf
	v_min_u32_dpp v93, v92, v92 quad_perm:[2,3,0,1] row_mask:0xf bank_mask:0xf
	v_min_u32_dpp v95, v94, v94 quad_perm:[2,3,0,1] row_mask:0xf bank_mask:0xf
	v_min_u32_dpp v80, v81, v81 row_half_mirror row_mask:0xf bank_mask:0xf
	v_min_u32_dpp v82, v83, v83 row_half_mirror row_mask:0xf bank_mask:0xf
	v_min_u32_dpp v84, v85, v85 row_half_mirror row_mask:0xf bank_mask:0xf
	v_min_u32_dpp v86, v87, v87 row_half_mirror row_mask:0xf bank_mask:0xf
	v_min_u32_dpp v88, v89, v89 row_half_mirror row_mask:0xf bank_mask:0xf
	v_min_u32_dpp v90, v91, v91 row_half_mirror row_mask:0xf bank_mask:0xf
	v_min_u32_dpp v92, v93, v93 row_half_mirror row_mask:0xf bank_mask:0xf
	v_min_u32_dpp v94, v95, v95 row_half_mirror row_mask:0xf bank_mask:0xf
	v_min_u32_dpp v81, v80, v80 row_mirror row_mask:0xf bank_mask:0xf
	v_min_u32_dpp v83, v82, v82 row_mirror row_mask:0xf bank_mask:0xf
	v_min_u32_dpp v85, v84, v84 row_mirror row_mask:0xf bank_mask:0xf
	v_min_u32_dpp v87, v86, v86 row_mirror row_mask:0xf bank_mask:0xf
	v_min_u32_dpp v89, v88, v88 row_mirror row_mask:0xf bank_mask:0xf
	v_min_u32_dpp v91, v90, v90 row_mirror row_mask:0xf bank_mask:0xf
	v_min_u32_dpp v93, v92, v92 row_mirror row_mask:0xf bank_mask:0xf
	v_min_u32_dpp v95, v94, v94 row_mirror row_mask:0xf bank_mask:0xf
	v_mov_b32_e32 v80, v81
	v_mov_b32_e32 v82, v83
	v_mov_b32_e32 v84, v85
	v_mov_b32_e32 v86, v87
	v_mov_b32_e32 v88, v89
	v_mov_b32_e32 v90, v91
	v_mov_b32_e32 v92, v93
	v_mov_b32_e32 v94, v95
	v_permlane16_swap_b32_e32 v81, v80
	v_permlane16_swap_b32_e32 v83, v82
	v_permlane16_swap_b32_e32 v85, v84
	v_permlane16_swap_b32_e32 v87, v86
	v_permlane16_swap_b32_e32 v89, v88
	v_permlane16_swap_b32_e32 v91, v90
	v_permlane16_swap_b32_e32 v93, v92
	v_permlane16_swap_b32_e32 v95, v94
	v_min_u32_e32 v81, v81, v80
	v_min_u32_e32 v83, v83, v82
	v_min_u32_e32 v85, v85, v84
	v_min_u32_e32 v87, v87, v86
	v_min_u32_e32 v89, v89, v88
	v_min_u32_e32 v91, v91, v90
	v_min_u32_e32 v93, v93, v92
	v_min_u32_e32 v95, v95, v94
	v_mov_b32_e32 v80, v81
	v_mov_b32_e32 v82, v83
	v_mov_b32_e32 v84, v85
	v_mov_b32_e32 v86, v87
	v_mov_b32_e32 v88, v89
	v_mov_b32_e32 v90, v91
	v_mov_b32_e32 v92, v93
	v_mov_b32_e32 v94, v95
	v_permlane32_swap_b32_e32 v81, v80
	v_permlane32_swap_b32_e32 v83, v82
	v_permlane32_swap_b32_e32 v85, v84
	v_permlane32_swap_b32_e32 v87, v86
	v_permlane32_swap_b32_e32 v89, v88
	v_permlane32_swap_b32_e32 v91, v90
	v_permlane32_swap_b32_e32 v93, v92
	v_permlane32_swap_b32_e32 v95, v94
	v_min_u32_e32 v65, v81, v80
	v_min_u32_e32 v67, v83, v82
	v_min_u32_e32 v69, v85, v84
	v_min_u32_e32 v71, v87, v86
	v_min_u32_e32 v73, v89, v88
	v_min_u32_e32 v75, v91, v90
	v_min_u32_e32 v77, v93, v92
	v_min_u32_e32 v79, v95, v94
	v_and_b32_e32 v80, 63, v65
	v_and_b32_e32 v82, 63, v67
	v_and_b32_e32 v84, 63, v69
	v_and_b32_e32 v86, 63, v71
	v_and_b32_e32 v88, 63, v73
	v_and_b32_e32 v90, 63, v75
	v_and_b32_e32 v92, 63, v77
	v_and_b32_e32 v94, 63, v79
	v_lshrrev_b32_e32 v81, 6, v65
	v_lshrrev_b32_e32 v83, 6, v67
	v_lshrrev_b32_e32 v85, 6, v69
	v_lshrrev_b32_e32 v87, 6, v71
	v_lshrrev_b32_e32 v89, 6, v73
	v_lshrrev_b32_e32 v91, 6, v75
	v_lshrrev_b32_e32 v93, 6, v77
	v_lshrrev_b32_e32 v95, 6, v79
	v_lshlrev_b32_e64 v81, v81, 1
	v_lshlrev_b32_e64 v83, v83, 1
	v_lshlrev_b32_e64 v85, v85, 1
	v_lshlrev_b32_e64 v87, v87, 1
	v_lshlrev_b32_e64 v89, v89, 1
	v_lshlrev_b32_e64 v91, v91, 1
	v_lshlrev_b32_e64 v93, v93, 1
	v_lshlrev_b32_e64 v95, v95, 1
	v_cmp_eq_u32_e64 s[4:5], v80, v227
	v_cmp_eq_u32_e64 s[6:7], v82, v227
	v_cmp_eq_u32_e64 s[8:9], v84, v227
	v_cmp_eq_u32_e64 s[10:11], v86, v227
	v_cmp_eq_u32_e64 s[12:13], v88, v227
	v_cmp_eq_u32_e64 s[14:15], v90, v227
	v_cmp_eq_u32_e64 s[16:17], v92, v227
	v_cmp_eq_u32_e64 s[18:19], v94, v227
	v_cndmask_b32_e64 v81, 0, v81, s[4:5]
	v_cndmask_b32_e64 v83, 0, v83, s[6:7]
	v_cndmask_b32_e64 v85, 0, v85, s[8:9]
	v_cndmask_b32_e64 v87, 0, v87, s[10:11]
	v_cndmask_b32_e64 v89, 0, v89, s[12:13]
	v_cndmask_b32_e64 v91, 0, v91, s[14:15]
	v_cndmask_b32_e64 v93, 0, v93, s[16:17]
	v_cndmask_b32_e64 v95, 0, v95, s[18:19]
	v_or_b32_e32 v49, v81, v49
	v_or_b32_e32 v42, v83, v42
	v_or_b32_e32 v33, v85, v33
	v_or_b32_e32 v24, v87, v24
	v_or_b32_e32 v20, v89, v20
	v_or_b32_e32 v5, v91, v5
	v_or_b32_e32 v2, v93, v2
	v_or_b32_e32 v1, v95, v1
	s_add_i32 s30, s30, -1
	s_cmp_eq_u32 s30, 0
	s_cbranch_scc0 .LBB0_2301
